# removed redundant vmcnt(0) before the attention pass-top barrier (store acks overlap next pass's loads); on top of LN/rope/stat load batching and attention epilogue/DMA placement
# speedup vs baseline: 1.0128x; 1.0128x over previous
.LBB0_713:
	s_mov_b32 m0, s31
	s_xor_b64 s[14:15], s[16:17], -1
	s_and_b64 s[16:17], s[16:17], exec
	s_barrier
	global_load_lds_dwordx4 v[174:175], off
	s_mov_b32 m0, s37
	s_cselect_b32 s6, s44, s43
	global_load_lds_dwordx4 v[176:177], off
	s_add_i32 m0, s41, 0x4000
	s_lshr_b32 s52, s6, 6
	global_load_lds_dwordx4 v[178:179], off
	s_add_i32 m0, s31, 0x6000
	v_mov_b32_e32 v2, v194
	global_load_lds_dwordx4 v[180:181], off
	s_add_i32 m0, s31, 0x6400
	v_mov_b32_e32 v14, v0
	global_load_lds_dwordx4 v[182:183], off
	s_mov_b32 m0, s35
	v_mov_b32_e32 v15, v0
	global_load_lds_dwordx4 v[184:185], off
	s_mov_b32 m0, s38
	s_waitcnt lgkmcnt(0)
	v_mov_b32_e32 v1, v0
	global_load_lds_dwordx4 v[186:187], off
	s_add_i32 m0, s41, 0xe000
	v_mov_b32_e32 v4, v0
	global_load_lds_dwordx4 v[188:189], off
	s_add_i32 m0, s35, 0x6000
	v_mov_b32_e32 v5, v0
	global_load_lds_dwordx4 v[190:191], off
	s_add_i32 m0, s35, 0x6400
	s_add_u32 s16, s48, s6
	s_addc_u32 s17, s49, 0
	s_mul_i32 s18, s17, 0x1800
	s_mul_hi_u32 s19, s16, 0x1800
	s_add_i32 s19, s19, s18
	s_mul_i32 s18, s16, 0x1800
	s_add_u32 s18, s50, s18
	global_load_lds_dwordx4 v[192:193], off
	s_addc_u32 s19, s51, s19
	v_ashrrev_i32_e32 v3, 31, v2
	v_lshl_add_u64 v[2:3], v[2:3], 1, s[18:19]
	global_load_dwordx4 v[112:115], v[2:3], off
	global_load_dwordx4 v[116:119], v[2:3], off offset:32
	global_load_dwordx4 v[120:123], v[2:3], off offset:64
	global_load_dwordx4 v[124:127], v[2:3], off offset:96
	global_load_dwordx4 v[128:131], v[2:3], off offset:128
	global_load_dwordx4 v[132:135], v[2:3], off offset:160
	global_load_dwordx4 v[136:139], v[2:3], off offset:192
	global_load_dwordx4 v[140:143], v[2:3], off offset:224
	global_load_dwordx4 v[144:147], v[2:3], off offset:256
	global_load_dwordx4 v[148:151], v[2:3], off offset:288
	global_load_dwordx4 v[152:155], v[2:3], off offset:320
	global_load_dwordx4 v[156:159], v[2:3], off offset:352
	s_add_i32 s6, s6, s36
	s_waitcnt vmcnt(0)
	v_mov_b32_e32 v2, v0
	v_mov_b32_e32 v3, v0
	v_mov_b32_e32 v6, v0
	v_mov_b32_e32 v7, v0
	v_mov_b32_e32 v8, v0
	v_mov_b32_e32 v9, v0
	v_mov_b32_e32 v10, v0
	v_mov_b32_e32 v11, v0
	v_mov_b32_e32 v12, v0
	v_mov_b32_e32 v13, v0
	s_or_b32 s59, s6, 63
	v_mov_b64_e32 v[62:63], v[14:15]
	v_mov_b64_e32 v[78:79], v[14:15]
	v_mov_b64_e32 v[94:95], v[14:15]
	v_mov_b64_e32 v[110:111], v[14:15]
	s_mov_b32 s53, 63
	s_mov_b32 s54, 0
	s_add_i32 s55, s52, 4
	s_or_b32 s58, s52, 3
	v_add_u32_e32 v216, s59, v213
	v_mov_b32_e32 v218, 0
	v_mov_b32_e32 v217, 0xf149f2ca
	s_mov_b32 s61, 2
	s_mov_b32 s60, -4
	v_mov_b64_e32 v[60:61], v[12:13]
	v_mov_b64_e32 v[58:59], v[10:11]
	v_mov_b64_e32 v[56:57], v[8:9]
	v_mov_b64_e32 v[54:55], v[6:7]
	v_mov_b64_e32 v[52:53], v[4:5]
	s_waitcnt vmcnt(0)
	s_waitcnt lgkmcnt(0)
	s_barrier
	v_mov_b64_e32 v[50:51], v[2:3]
	v_mov_b64_e32 v[48:49], v[0:1]
	v_mov_b64_e32 v[76:77], v[12:13]
	v_mov_b64_e32 v[74:75], v[10:11]
	v_mov_b64_e32 v[72:73], v[8:9]
	v_mov_b64_e32 v[70:71], v[6:7]
	v_mov_b64_e32 v[68:69], v[4:5]
	v_mov_b64_e32 v[66:67], v[2:3]
	v_mov_b64_e32 v[64:65], v[0:1]
	v_mov_b64_e32 v[92:93], v[12:13]
	v_mov_b64_e32 v[90:91], v[10:11]
	v_mov_b64_e32 v[88:89], v[8:9]
	v_mov_b64_e32 v[86:87], v[6:7]
	v_mov_b64_e32 v[84:85], v[4:5]
	v_mov_b64_e32 v[82:83], v[2:3]
	v_mov_b64_e32 v[80:81], v[0:1]
	v_mov_b64_e32 v[108:109], v[12:13]
	v_mov_b64_e32 v[106:107], v[10:11]
	v_mov_b64_e32 v[104:105], v[8:9]
	v_mov_b64_e32 v[102:103], v[6:7]
	v_mov_b64_e32 v[100:101], v[4:5]
	v_mov_b64_e32 v[98:99], v[2:3]
	v_mov_b64_e32 v[96:97], v[0:1]
	s_branch .LBB0_717

.LBB0_1484:
	s_mov_b32 m0, s50
	s_and_b64 s[20:21], s[38:39], exec
	s_barrier
	global_load_lds_dwordx4 v[158:159], off
	s_mov_b32 m0, s53
	s_cselect_b32 s84, s64, s63
	global_load_lds_dwordx4 v[160:161], off
	s_add_i32 m0, s50, 0x4000
	s_add_i32 s20, s84, 0x100
	global_load_lds_dwordx4 v[162:163], off
	s_mov_b32 m0, s54
	v_cmp_gt_i32_e64 s[20:21], s20, v156
	global_load_lds_dwordx4 v[164:165], off
	s_mov_b32 m0, s55
	v_mov_b32_e32 v1, 0
	global_load_lds_dwordx4 v[166:167], off
	s_mov_b32 m0, s58
	v_mov_b32_e32 v2, 0
	global_load_lds_dwordx4 v[168:169], off
	s_mov_b32 m0, s59
	s_nop 0
	global_load_lds_dwordx4 v[170:171], off
	s_mov_b32 m0, s60
	s_nop 0
	global_load_lds_dwordx4 v[172:173], off
	s_and_saveexec_b64 s[36:37], s[20:21]
	s_cbranch_execz .LBB0_1486
	global_load_dword v2, v[174:175], off
	s_waitcnt vmcnt(0)
	v_add_f32_e32 v2, 0, v2
